# prompt indexer head loop unrolled: query fragments of a head in flight before its MFMAs, weight quads reuse fragment registers, next head requested during relu/FMA
# speedup vs baseline: 1.0092x; 1.0023x over previous
.LBB0_1001:
	v_mov_b32_e32 v150, 0
	s_mov_b32 s10, 8
	s_mov_b32 s11, s5
	v_mov_b32_e32 v146, v1
	v_mov_b32_e32 v151, v150
	v_mov_b32_e32 v164, v150
	v_mov_b32_e32 v165, v150
	v_mov_b32_e32 v162, v150
	v_mov_b32_e32 v163, v150
	v_mov_b32_e32 v160, v150
	v_mov_b32_e32 v161, v150
	v_mov_b32_e32 v158, v150
	v_mov_b32_e32 v159, v150
	v_mov_b32_e32 v156, v150
	v_mov_b32_e32 v157, v150
	v_mov_b32_e32 v154, v150
	v_mov_b32_e32 v155, v150
	v_mov_b32_e32 v152, v150
	v_mov_b32_e32 v153, v150
	v_add_u32_e32 v147, v1, v229
	v_add_u32_e32 v148, s5, v229
	v_add_u32_e32 v148, 0x20800, v148
	ds_read_b128 v[166:169], v147 offset:0
	ds_read_b128 v[170:173], v147 offset:32
	ds_read_b128 v[174:177], v147 offset:64
	ds_read_b128 v[178:181], v147 offset:96
	s_waitcnt vmcnt(7) lgkmcnt(3)
	v_mfma_f32_32x32x16_f16 v[2:17], v[166:169], v[18:21], 0
	ds_read_b128 v[166:169], v148 offset:0
	s_waitcnt vmcnt(6) lgkmcnt(3)
	v_mfma_f32_32x32x16_f16 v[2:17], v[170:173], v[22:25], v[2:17]
	ds_read_b128 v[170:173], v148 offset:32
	s_waitcnt vmcnt(5) lgkmcnt(3)
	v_mfma_f32_32x32x16_f16 v[2:17], v[174:177], v[26:29], v[2:17]
	ds_read_b128 v[174:177], v148 offset:64
	s_waitcnt vmcnt(4) lgkmcnt(3)
	v_mfma_f32_32x32x16_f16 v[2:17], v[178:181], v[30:33], v[2:17]
	ds_read_b128 v[178:181], v148 offset:96
	s_nop 10
	s_waitcnt lgkmcnt(3)
	v_max_f32_e32 v2, 0, v2
	v_max_f32_e32 v3, 0, v3
	v_pk_fma_f32 v[164:165], v[166:167], v[2:3], v[164:165]
	v_max_f32_e32 v4, 0, v4
	v_max_f32_e32 v5, 0, v5
	v_pk_fma_f32 v[162:163], v[168:169], v[4:5], v[162:163]
	ds_read_b128 v[166:169], v147 offset:128
	s_waitcnt lgkmcnt(3)
	v_max_f32_e32 v6, 0, v6
	v_max_f32_e32 v7, 0, v7
	v_pk_fma_f32 v[160:161], v[170:171], v[6:7], v[160:161]
	v_max_f32_e32 v8, 0, v8
	v_max_f32_e32 v9, 0, v9
	v_pk_fma_f32 v[158:159], v[172:173], v[8:9], v[158:159]
	ds_read_b128 v[170:173], v147 offset:160
	s_waitcnt lgkmcnt(3)
	v_max_f32_e32 v10, 0, v10
	v_max_f32_e32 v11, 0, v11
	v_pk_fma_f32 v[156:157], v[174:175], v[10:11], v[156:157]
	v_max_f32_e32 v12, 0, v12
	v_max_f32_e32 v13, 0, v13
	v_pk_fma_f32 v[154:155], v[176:177], v[12:13], v[154:155]
	ds_read_b128 v[174:177], v147 offset:192
	s_waitcnt lgkmcnt(3)
	v_max_f32_e32 v14, 0, v14
	v_max_f32_e32 v15, 0, v15
	v_pk_fma_f32 v[152:153], v[178:179], v[14:15], v[152:153]
	v_max_f32_e32 v16, 0, v16
	v_max_f32_e32 v17, 0, v17
	v_pk_fma_f32 v[150:151], v[180:181], v[16:17], v[150:151]
	ds_read_b128 v[178:181], v147 offset:224
	s_waitcnt lgkmcnt(3)
	v_mfma_f32_32x32x16_f16 v[2:17], v[166:169], v[18:21], 0
	ds_read_b128 v[166:169], v148 offset:512
	s_waitcnt lgkmcnt(3)
	v_mfma_f32_32x32x16_f16 v[2:17], v[170:173], v[22:25], v[2:17]
	ds_read_b128 v[170:173], v148 offset:544
	s_waitcnt lgkmcnt(3)
	v_mfma_f32_32x32x16_f16 v[2:17], v[174:177], v[26:29], v[2:17]
	ds_read_b128 v[174:177], v148 offset:576
	s_waitcnt lgkmcnt(3)
	v_mfma_f32_32x32x16_f16 v[2:17], v[178:181], v[30:33], v[2:17]
	ds_read_b128 v[178:181], v148 offset:608
	s_nop 10
	s_waitcnt lgkmcnt(3)
	v_max_f32_e32 v2, 0, v2
	v_max_f32_e32 v3, 0, v3
	v_pk_fma_f32 v[164:165], v[166:167], v[2:3], v[164:165]
	v_max_f32_e32 v4, 0, v4
	v_max_f32_e32 v5, 0, v5
	v_pk_fma_f32 v[162:163], v[168:169], v[4:5], v[162:163]
	ds_read_b128 v[166:169], v147 offset:256
	s_waitcnt lgkmcnt(3)
	v_max_f32_e32 v6, 0, v6
	v_max_f32_e32 v7, 0, v7
	v_pk_fma_f32 v[160:161], v[170:171], v[6:7], v[160:161]
	v_max_f32_e32 v8, 0, v8
	v_max_f32_e32 v9, 0, v9
	v_pk_fma_f32 v[158:159], v[172:173], v[8:9], v[158:159]
	ds_read_b128 v[170:173], v147 offset:288
	s_waitcnt lgkmcnt(3)
	v_max_f32_e32 v10, 0, v10
	v_max_f32_e32 v11, 0, v11
	v_pk_fma_f32 v[156:157], v[174:175], v[10:11], v[156:157]
	v_max_f32_e32 v12, 0, v12
	v_max_f32_e32 v13, 0, v13
	v_pk_fma_f32 v[154:155], v[176:177], v[12:13], v[154:155]
	ds_read_b128 v[174:177], v147 offset:320
	s_waitcnt lgkmcnt(3)
	v_max_f32_e32 v14, 0, v14
	v_max_f32_e32 v15, 0, v15
	v_pk_fma_f32 v[152:153], v[178:179], v[14:15], v[152:153]
	v_max_f32_e32 v16, 0, v16
	v_max_f32_e32 v17, 0, v17
	v_pk_fma_f32 v[150:151], v[180:181], v[16:17], v[150:151]
	ds_read_b128 v[178:181], v147 offset:352
	s_waitcnt lgkmcnt(3)
	v_mfma_f32_32x32x16_f16 v[2:17], v[166:169], v[18:21], 0
	ds_read_b128 v[166:169], v148 offset:1024
	s_waitcnt lgkmcnt(3)
	v_mfma_f32_32x32x16_f16 v[2:17], v[170:173], v[22:25], v[2:17]
	ds_read_b128 v[170:173], v148 offset:1056
	s_waitcnt lgkmcnt(3)
	v_mfma_f32_32x32x16_f16 v[2:17], v[174:177], v[26:29], v[2:17]
	ds_read_b128 v[174:177], v148 offset:1088
	s_waitcnt lgkmcnt(3)
	v_mfma_f32_32x32x16_f16 v[2:17], v[178:181], v[30:33], v[2:17]
	ds_read_b128 v[178:181], v148 offset:1120
	s_nop 10
	s_waitcnt lgkmcnt(3)
	v_max_f32_e32 v2, 0, v2
	v_max_f32_e32 v3, 0, v3
	v_pk_fma_f32 v[164:165], v[166:167], v[2:3], v[164:165]
	v_max_f32_e32 v4, 0, v4
	v_max_f32_e32 v5, 0, v5
	v_pk_fma_f32 v[162:163], v[168:169], v[4:5], v[162:163]
	ds_read_b128 v[166:169], v147 offset:384
	s_waitcnt lgkmcnt(3)
	v_max_f32_e32 v6, 0, v6
	v_max_f32_e32 v7, 0, v7
	v_pk_fma_f32 v[160:161], v[170:171], v[6:7], v[160:161]
	v_max_f32_e32 v8, 0, v8
	v_max_f32_e32 v9, 0, v9
	v_pk_fma_f32 v[158:159], v[172:173], v[8:9], v[158:159]
	ds_read_b128 v[170:173], v147 offset:416
	s_waitcnt lgkmcnt(3)
	v_max_f32_e32 v10, 0, v10
	v_max_f32_e32 v11, 0, v11
	v_pk_fma_f32 v[156:157], v[174:175], v[10:11], v[156:157]
	v_max_f32_e32 v12, 0, v12
	v_max_f32_e32 v13, 0, v13
	v_pk_fma_f32 v[154:155], v[176:177], v[12:13], v[154:155]
	ds_read_b128 v[174:177], v147 offset:448
	s_waitcnt lgkmcnt(3)
	v_max_f32_e32 v14, 0, v14
	v_max_f32_e32 v15, 0, v15
	v_pk_fma_f32 v[152:153], v[178:179], v[14:15], v[152:153]
	v_max_f32_e32 v16, 0, v16
	v_max_f32_e32 v17, 0, v17
	v_pk_fma_f32 v[150:151], v[180:181], v[16:17], v[150:151]
	ds_read_b128 v[178:181], v147 offset:480
	s_waitcnt lgkmcnt(3)
	v_mfma_f32_32x32x16_f16 v[2:17], v[166:169], v[18:21], 0
	ds_read_b128 v[166:169], v148 offset:1536
	s_waitcnt lgkmcnt(3)
	v_mfma_f32_32x32x16_f16 v[2:17], v[170:173], v[22:25], v[2:17]
	ds_read_b128 v[170:173], v148 offset:1568
	s_waitcnt lgkmcnt(3)
	v_mfma_f32_32x32x16_f16 v[2:17], v[174:177], v[26:29], v[2:17]
	ds_read_b128 v[174:177], v148 offset:1600
	s_waitcnt lgkmcnt(3)
	v_mfma_f32_32x32x16_f16 v[2:17], v[178:181], v[30:33], v[2:17]
	ds_read_b128 v[178:181], v148 offset:1632
	s_nop 10
	s_waitcnt lgkmcnt(3)
	v_max_f32_e32 v2, 0, v2
	v_max_f32_e32 v3, 0, v3
	v_pk_fma_f32 v[164:165], v[166:167], v[2:3], v[164:165]
	v_max_f32_e32 v4, 0, v4
	v_max_f32_e32 v5, 0, v5
	v_pk_fma_f32 v[162:163], v[168:169], v[4:5], v[162:163]
	ds_read_b128 v[166:169], v147 offset:512
	s_waitcnt lgkmcnt(3)
	v_max_f32_e32 v6, 0, v6
	v_max_f32_e32 v7, 0, v7
	v_pk_fma_f32 v[160:161], v[170:171], v[6:7], v[160:161]
	v_max_f32_e32 v8, 0, v8
	v_max_f32_e32 v9, 0, v9
	v_pk_fma_f32 v[158:159], v[172:173], v[8:9], v[158:159]
	ds_read_b128 v[170:173], v147 offset:544
	s_waitcnt lgkmcnt(3)
	v_max_f32_e32 v10, 0, v10
	v_max_f32_e32 v11, 0, v11
	v_pk_fma_f32 v[156:157], v[174:175], v[10:11], v[156:157]
	v_max_f32_e32 v12, 0, v12
	v_max_f32_e32 v13, 0, v13
	v_pk_fma_f32 v[154:155], v[176:177], v[12:13], v[154:155]
	ds_read_b128 v[174:177], v147 offset:576
	s_waitcnt lgkmcnt(3)
	v_max_f32_e32 v14, 0, v14
	v_max_f32_e32 v15, 0, v15
	v_pk_fma_f32 v[152:153], v[178:179], v[14:15], v[152:153]
	v_max_f32_e32 v16, 0, v16
	v_max_f32_e32 v17, 0, v17
	v_pk_fma_f32 v[150:151], v[180:181], v[16:17], v[150:151]
	ds_read_b128 v[178:181], v147 offset:608
	s_waitcnt lgkmcnt(3)
	v_mfma_f32_32x32x16_f16 v[2:17], v[166:169], v[18:21], 0
	ds_read_b128 v[166:169], v148 offset:2048
	s_waitcnt lgkmcnt(3)
	v_mfma_f32_32x32x16_f16 v[2:17], v[170:173], v[22:25], v[2:17]
	ds_read_b128 v[170:173], v148 offset:2080
	s_waitcnt lgkmcnt(3)
	v_mfma_f32_32x32x16_f16 v[2:17], v[174:177], v[26:29], v[2:17]
	ds_read_b128 v[174:177], v148 offset:2112
	s_waitcnt lgkmcnt(3)
	v_mfma_f32_32x32x16_f16 v[2:17], v[178:181], v[30:33], v[2:17]
	ds_read_b128 v[178:181], v148 offset:2144
	s_nop 10
	s_waitcnt lgkmcnt(3)
	v_max_f32_e32 v2, 0, v2
	v_max_f32_e32 v3, 0, v3
	v_pk_fma_f32 v[164:165], v[166:167], v[2:3], v[164:165]
	v_max_f32_e32 v4, 0, v4
	v_max_f32_e32 v5, 0, v5
	v_pk_fma_f32 v[162:163], v[168:169], v[4:5], v[162:163]
	ds_read_b128 v[166:169], v147 offset:640
	s_waitcnt lgkmcnt(3)
	v_max_f32_e32 v6, 0, v6
	v_max_f32_e32 v7, 0, v7
	v_pk_fma_f32 v[160:161], v[170:171], v[6:7], v[160:161]
	v_max_f32_e32 v8, 0, v8
	v_max_f32_e32 v9, 0, v9
	v_pk_fma_f32 v[158:159], v[172:173], v[8:9], v[158:159]
	ds_read_b128 v[170:173], v147 offset:672
	s_waitcnt lgkmcnt(3)
	v_max_f32_e32 v10, 0, v10
	v_max_f32_e32 v11, 0, v11
	v_pk_fma_f32 v[156:157], v[174:175], v[10:11], v[156:157]
	v_max_f32_e32 v12, 0, v12
	v_max_f32_e32 v13, 0, v13
	v_pk_fma_f32 v[154:155], v[176:177], v[12:13], v[154:155]
	ds_read_b128 v[174:177], v147 offset:704
	s_waitcnt lgkmcnt(3)
	v_max_f32_e32 v14, 0, v14
	v_max_f32_e32 v15, 0, v15
	v_pk_fma_f32 v[152:153], v[178:179], v[14:15], v[152:153]
	v_max_f32_e32 v16, 0, v16
	v_max_f32_e32 v17, 0, v17
	v_pk_fma_f32 v[150:151], v[180:181], v[16:17], v[150:151]
	ds_read_b128 v[178:181], v147 offset:736
	s_waitcnt lgkmcnt(3)
	v_mfma_f32_32x32x16_f16 v[2:17], v[166:169], v[18:21], 0
	ds_read_b128 v[166:169], v148 offset:2560
	s_waitcnt lgkmcnt(3)
	v_mfma_f32_32x32x16_f16 v[2:17], v[170:173], v[22:25], v[2:17]
	ds_read_b128 v[170:173], v148 offset:2592
	s_waitcnt lgkmcnt(3)
	v_mfma_f32_32x32x16_f16 v[2:17], v[174:177], v[26:29], v[2:17]
	ds_read_b128 v[174:177], v148 offset:2624
	s_waitcnt lgkmcnt(3)
	v_mfma_f32_32x32x16_f16 v[2:17], v[178:181], v[30:33], v[2:17]
	ds_read_b128 v[178:181], v148 offset:2656
	s_nop 10
	s_waitcnt lgkmcnt(3)
	v_max_f32_e32 v2, 0, v2
	v_max_f32_e32 v3, 0, v3
	v_pk_fma_f32 v[164:165], v[166:167], v[2:3], v[164:165]
	v_max_f32_e32 v4, 0, v4
	v_max_f32_e32 v5, 0, v5
	v_pk_fma_f32 v[162:163], v[168:169], v[4:5], v[162:163]
	ds_read_b128 v[166:169], v147 offset:768
	s_waitcnt lgkmcnt(3)
	v_max_f32_e32 v6, 0, v6
	v_max_f32_e32 v7, 0, v7
	v_pk_fma_f32 v[160:161], v[170:171], v[6:7], v[160:161]
	v_max_f32_e32 v8, 0, v8
	v_max_f32_e32 v9, 0, v9
	v_pk_fma_f32 v[158:159], v[172:173], v[8:9], v[158:159]
	ds_read_b128 v[170:173], v147 offset:800
	s_waitcnt lgkmcnt(3)
	v_max_f32_e32 v10, 0, v10
	v_max_f32_e32 v11, 0, v11
	v_pk_fma_f32 v[156:157], v[174:175], v[10:11], v[156:157]
	v_max_f32_e32 v12, 0, v12
	v_max_f32_e32 v13, 0, v13
	v_pk_fma_f32 v[154:155], v[176:177], v[12:13], v[154:155]
	ds_read_b128 v[174:177], v147 offset:832
	s_waitcnt lgkmcnt(3)
	v_max_f32_e32 v14, 0, v14
	v_max_f32_e32 v15, 0, v15
	v_pk_fma_f32 v[152:153], v[178:179], v[14:15], v[152:153]
	v_max_f32_e32 v16, 0, v16
	v_max_f32_e32 v17, 0, v17
	v_pk_fma_f32 v[150:151], v[180:181], v[16:17], v[150:151]
	ds_read_b128 v[178:181], v147 offset:864
	s_waitcnt lgkmcnt(3)
	v_mfma_f32_32x32x16_f16 v[2:17], v[166:169], v[18:21], 0
	ds_read_b128 v[166:169], v148 offset:3072
	s_waitcnt lgkmcnt(3)
	v_mfma_f32_32x32x16_f16 v[2:17], v[170:173], v[22:25], v[2:17]
	ds_read_b128 v[170:173], v148 offset:3104
	s_waitcnt lgkmcnt(3)
	v_mfma_f32_32x32x16_f16 v[2:17], v[174:177], v[26:29], v[2:17]
	ds_read_b128 v[174:177], v148 offset:3136
	s_waitcnt lgkmcnt(3)
	v_mfma_f32_32x32x16_f16 v[2:17], v[178:181], v[30:33], v[2:17]
	ds_read_b128 v[178:181], v148 offset:3168
	s_nop 10
	s_waitcnt lgkmcnt(3)
	v_max_f32_e32 v2, 0, v2
	v_max_f32_e32 v3, 0, v3
	v_pk_fma_f32 v[164:165], v[166:167], v[2:3], v[164:165]
	v_max_f32_e32 v4, 0, v4
	v_max_f32_e32 v5, 0, v5
	v_pk_fma_f32 v[162:163], v[168:169], v[4:5], v[162:163]
	ds_read_b128 v[166:169], v147 offset:896
	s_waitcnt lgkmcnt(3)
	v_max_f32_e32 v6, 0, v6
	v_max_f32_e32 v7, 0, v7
	v_pk_fma_f32 v[160:161], v[170:171], v[6:7], v[160:161]
	v_max_f32_e32 v8, 0, v8
	v_max_f32_e32 v9, 0, v9
	v_pk_fma_f32 v[158:159], v[172:173], v[8:9], v[158:159]
	ds_read_b128 v[170:173], v147 offset:928
	s_waitcnt lgkmcnt(3)
	v_max_f32_e32 v10, 0, v10
	v_max_f32_e32 v11, 0, v11
	v_pk_fma_f32 v[156:157], v[174:175], v[10:11], v[156:157]
	v_max_f32_e32 v12, 0, v12
	v_max_f32_e32 v13, 0, v13
	v_pk_fma_f32 v[154:155], v[176:177], v[12:13], v[154:155]
	ds_read_b128 v[174:177], v147 offset:960
	s_waitcnt lgkmcnt(3)
	v_max_f32_e32 v14, 0, v14
	v_max_f32_e32 v15, 0, v15
	v_pk_fma_f32 v[152:153], v[178:179], v[14:15], v[152:153]
	v_max_f32_e32 v16, 0, v16
	v_max_f32_e32 v17, 0, v17
	v_pk_fma_f32 v[150:151], v[180:181], v[16:17], v[150:151]
	ds_read_b128 v[178:181], v147 offset:992
	s_waitcnt lgkmcnt(3)
	v_mfma_f32_32x32x16_f16 v[2:17], v[166:169], v[18:21], 0
	ds_read_b128 v[166:169], v148 offset:3584
	s_waitcnt lgkmcnt(3)
	v_mfma_f32_32x32x16_f16 v[2:17], v[170:173], v[22:25], v[2:17]
	ds_read_b128 v[170:173], v148 offset:3616
	s_waitcnt lgkmcnt(3)
	v_mfma_f32_32x32x16_f16 v[2:17], v[174:177], v[26:29], v[2:17]
	ds_read_b128 v[174:177], v148 offset:3648
	s_waitcnt lgkmcnt(3)
	v_mfma_f32_32x32x16_f16 v[2:17], v[178:181], v[30:33], v[2:17]
	ds_read_b128 v[178:181], v148 offset:3680
	s_nop 10
	s_waitcnt lgkmcnt(3)
	v_max_f32_e32 v2, 0, v2
	v_max_f32_e32 v3, 0, v3
	v_pk_fma_f32 v[164:165], v[166:167], v[2:3], v[164:165]
	v_max_f32_e32 v4, 0, v4
	v_max_f32_e32 v5, 0, v5
	v_pk_fma_f32 v[162:163], v[168:169], v[4:5], v[162:163]
	s_waitcnt lgkmcnt(2)
	v_max_f32_e32 v6, 0, v6
	v_max_f32_e32 v7, 0, v7
	v_pk_fma_f32 v[160:161], v[170:171], v[6:7], v[160:161]
	v_max_f32_e32 v8, 0, v8
	v_max_f32_e32 v9, 0, v9
	v_pk_fma_f32 v[158:159], v[172:173], v[8:9], v[158:159]
	s_waitcnt lgkmcnt(1)
	v_max_f32_e32 v10, 0, v10
	v_max_f32_e32 v11, 0, v11
	v_pk_fma_f32 v[156:157], v[174:175], v[10:11], v[156:157]
	v_max_f32_e32 v12, 0, v12
	v_max_f32_e32 v13, 0, v13
	v_pk_fma_f32 v[154:155], v[176:177], v[12:13], v[154:155]
	s_waitcnt lgkmcnt(0)
	v_max_f32_e32 v14, 0, v14
	v_max_f32_e32 v15, 0, v15
	v_pk_fma_f32 v[152:153], v[178:179], v[14:15], v[152:153]
	v_max_f32_e32 v16, 0, v16
	v_max_f32_e32 v17, 0, v17
	v_pk_fma_f32 v[150:151], v[180:181], v[16:17], v[150:151]
	s_lshl_b32 s10, s14, 7
	s_ashr_i32 s11, s10, 31
	v_lshl_add_u64 v[146:147], s[10:11], 2, v[232:233]
	v_lshl_add_u64 v[2:3], v[146:147], 0, v[198:199]
	global_store_dword v[2:3], v165, off nt
	v_lshl_add_u64 v[2:3], v[146:147], 0, v[200:201]
	global_store_dword v[2:3], v162, off nt
	v_lshl_add_u64 v[2:3], v[146:147], 0, v[202:203]
	global_store_dword v[2:3], v163, off nt
	v_lshl_add_u64 v[2:3], v[146:147], 0, v[204:205]
	global_store_dword v[2:3], v160, off nt
	v_lshl_add_u64 v[2:3], v[146:147], 0, v[206:207]
	global_store_dword v[2:3], v161, off nt
	v_lshl_add_u64 v[2:3], v[146:147], 0, v[208:209]
	global_store_dword v[2:3], v158, off nt
	v_lshl_add_u64 v[2:3], v[146:147], 0, v[210:211]
	global_store_dword v[2:3], v159, off nt
	v_lshl_add_u64 v[2:3], v[146:147], 0, v[212:213]
	global_store_dword v[2:3], v156, off nt
	v_lshl_add_u64 v[2:3], v[146:147], 0, v[214:215]
	global_store_dword v[2:3], v157, off nt
	v_lshl_add_u64 v[2:3], v[146:147], 0, v[216:217]
	global_store_dword v[2:3], v154, off nt
	v_lshl_add_u64 v[2:3], v[146:147], 0, v[218:219]
	global_store_dword v[2:3], v155, off nt
	v_lshl_add_u64 v[2:3], v[146:147], 0, v[220:221]
	global_store_dword v[2:3], v152, off nt
	v_lshl_add_u64 v[2:3], v[146:147], 0, v[222:223]
	global_store_dword v[2:3], v153, off nt
	v_lshl_add_u64 v[2:3], v[146:147], 0, v[224:225]
	v_lshl_add_u64 v[148:149], v[146:147], 0, v[196:197]
	global_store_dword v[2:3], v150, off nt
	v_lshl_add_u64 v[2:3], v[146:147], 0, v[230:231]
	v_mov_b32_e32 v150, 0
	global_store_dword v[148:149], v164, off nt
	global_store_dword v[2:3], v151, off nt
	s_mov_b32 s10, 8
	s_mov_b32 s11, s5
	v_mov_b32_e32 v166, v1
	v_mov_b32_e32 v151, v150
	v_mov_b32_e32 v164, v150
	v_mov_b32_e32 v165, v150
	v_mov_b32_e32 v162, v150
	v_mov_b32_e32 v163, v150
	v_mov_b32_e32 v160, v150
	v_mov_b32_e32 v161, v150
	v_mov_b32_e32 v158, v150
	v_mov_b32_e32 v159, v150
	v_mov_b32_e32 v156, v150
	v_mov_b32_e32 v157, v150
	v_mov_b32_e32 v154, v150
	v_mov_b32_e32 v155, v150
	v_mov_b32_e32 v152, v150
	v_mov_b32_e32 v153, v150
	v_add_u32_e32 v167, v1, v229
	v_add_u32_e32 v184, s5, v229
	v_add_u32_e32 v184, 0x20800, v184
	ds_read_b128 v[168:171], v167 offset:0
	ds_read_b128 v[172:175], v167 offset:32
	ds_read_b128 v[176:179], v167 offset:64
	ds_read_b128 v[180:183], v167 offset:96
	s_waitcnt vmcnt(19) lgkmcnt(3)
	v_mfma_f32_32x32x16_f16 v[2:17], v[168:171], v[34:37], 0
	ds_read_b128 v[168:171], v184 offset:0
	s_waitcnt vmcnt(18) lgkmcnt(3)
	v_mfma_f32_32x32x16_f16 v[2:17], v[172:175], v[38:41], v[2:17]
	ds_read_b128 v[172:175], v184 offset:32
	s_waitcnt vmcnt(17) lgkmcnt(3)
	v_mfma_f32_32x32x16_f16 v[2:17], v[176:179], v[42:45], v[2:17]
	ds_read_b128 v[176:179], v184 offset:64
	s_waitcnt vmcnt(16) lgkmcnt(3)
	v_mfma_f32_32x32x16_f16 v[2:17], v[180:183], v[46:49], v[2:17]
	ds_read_b128 v[180:183], v184 offset:96
	s_nop 10
	s_waitcnt lgkmcnt(3)
	v_max_f32_e32 v2, 0, v2
	v_max_f32_e32 v3, 0, v3
	v_pk_fma_f32 v[164:165], v[168:169], v[2:3], v[164:165]
	v_max_f32_e32 v4, 0, v4
	v_max_f32_e32 v5, 0, v5
	v_pk_fma_f32 v[162:163], v[170:171], v[4:5], v[162:163]
	ds_read_b128 v[168:171], v167 offset:128
	s_waitcnt lgkmcnt(3)
	v_max_f32_e32 v6, 0, v6
	v_max_f32_e32 v7, 0, v7
	v_pk_fma_f32 v[160:161], v[172:173], v[6:7], v[160:161]
	v_max_f32_e32 v8, 0, v8
	v_max_f32_e32 v9, 0, v9
	v_pk_fma_f32 v[158:159], v[174:175], v[8:9], v[158:159]
	ds_read_b128 v[172:175], v167 offset:160
	s_waitcnt lgkmcnt(3)
	v_max_f32_e32 v10, 0, v10
	v_max_f32_e32 v11, 0, v11
	v_pk_fma_f32 v[156:157], v[176:177], v[10:11], v[156:157]
	v_max_f32_e32 v12, 0, v12
	v_max_f32_e32 v13, 0, v13
	v_pk_fma_f32 v[154:155], v[178:179], v[12:13], v[154:155]
	ds_read_b128 v[176:179], v167 offset:192
	s_waitcnt lgkmcnt(3)
	v_max_f32_e32 v14, 0, v14
	v_max_f32_e32 v15, 0, v15
	v_pk_fma_f32 v[152:153], v[180:181], v[14:15], v[152:153]
	v_max_f32_e32 v16, 0, v16
	v_max_f32_e32 v17, 0, v17
	v_pk_fma_f32 v[150:151], v[182:183], v[16:17], v[150:151]
	ds_read_b128 v[180:183], v167 offset:224
	s_waitcnt lgkmcnt(3)
	v_mfma_f32_32x32x16_f16 v[2:17], v[168:171], v[34:37], 0
	ds_read_b128 v[168:171], v184 offset:512
	s_waitcnt lgkmcnt(3)
	v_mfma_f32_32x32x16_f16 v[2:17], v[172:175], v[38:41], v[2:17]
	ds_read_b128 v[172:175], v184 offset:544
	s_waitcnt lgkmcnt(3)
	v_mfma_f32_32x32x16_f16 v[2:17], v[176:179], v[42:45], v[2:17]
	ds_read_b128 v[176:179], v184 offset:576
	s_waitcnt lgkmcnt(3)
	v_mfma_f32_32x32x16_f16 v[2:17], v[180:183], v[46:49], v[2:17]
	ds_read_b128 v[180:183], v184 offset:608
	s_nop 10
	s_waitcnt lgkmcnt(3)
	v_max_f32_e32 v2, 0, v2
	v_max_f32_e32 v3, 0, v3
	v_pk_fma_f32 v[164:165], v[168:169], v[2:3], v[164:165]
	v_max_f32_e32 v4, 0, v4
	v_max_f32_e32 v5, 0, v5
	v_pk_fma_f32 v[162:163], v[170:171], v[4:5], v[162:163]
	ds_read_b128 v[168:171], v167 offset:256
	s_waitcnt lgkmcnt(3)
	v_max_f32_e32 v6, 0, v6
	v_max_f32_e32 v7, 0, v7
	v_pk_fma_f32 v[160:161], v[172:173], v[6:7], v[160:161]
	v_max_f32_e32 v8, 0, v8
	v_max_f32_e32 v9, 0, v9
	v_pk_fma_f32 v[158:159], v[174:175], v[8:9], v[158:159]
	ds_read_b128 v[172:175], v167 offset:288
	s_waitcnt lgkmcnt(3)
	v_max_f32_e32 v10, 0, v10
	v_max_f32_e32 v11, 0, v11
	v_pk_fma_f32 v[156:157], v[176:177], v[10:11], v[156:157]
	v_max_f32_e32 v12, 0, v12
	v_max_f32_e32 v13, 0, v13
	v_pk_fma_f32 v[154:155], v[178:179], v[12:13], v[154:155]
	ds_read_b128 v[176:179], v167 offset:320
	s_waitcnt lgkmcnt(3)
	v_max_f32_e32 v14, 0, v14
	v_max_f32_e32 v15, 0, v15
	v_pk_fma_f32 v[152:153], v[180:181], v[14:15], v[152:153]
	v_max_f32_e32 v16, 0, v16
	v_max_f32_e32 v17, 0, v17
	v_pk_fma_f32 v[150:151], v[182:183], v[16:17], v[150:151]
	ds_read_b128 v[180:183], v167 offset:352
	s_waitcnt lgkmcnt(3)
	v_mfma_f32_32x32x16_f16 v[2:17], v[168:171], v[34:37], 0
	ds_read_b128 v[168:171], v184 offset:1024
	s_waitcnt lgkmcnt(3)
	v_mfma_f32_32x32x16_f16 v[2:17], v[172:175], v[38:41], v[2:17]
	ds_read_b128 v[172:175], v184 offset:1056
	s_waitcnt lgkmcnt(3)
	v_mfma_f32_32x32x16_f16 v[2:17], v[176:179], v[42:45], v[2:17]
	ds_read_b128 v[176:179], v184 offset:1088
	s_waitcnt lgkmcnt(3)
	v_mfma_f32_32x32x16_f16 v[2:17], v[180:183], v[46:49], v[2:17]
	ds_read_b128 v[180:183], v184 offset:1120
	s_nop 10
	s_waitcnt lgkmcnt(3)
	v_max_f32_e32 v2, 0, v2
	v_max_f32_e32 v3, 0, v3
	v_pk_fma_f32 v[164:165], v[168:169], v[2:3], v[164:165]
	v_max_f32_e32 v4, 0, v4
	v_max_f32_e32 v5, 0, v5
	v_pk_fma_f32 v[162:163], v[170:171], v[4:5], v[162:163]
	ds_read_b128 v[168:171], v167 offset:384
	s_waitcnt lgkmcnt(3)
	v_max_f32_e32 v6, 0, v6
	v_max_f32_e32 v7, 0, v7
	v_pk_fma_f32 v[160:161], v[172:173], v[6:7], v[160:161]
	v_max_f32_e32 v8, 0, v8
	v_max_f32_e32 v9, 0, v9
	v_pk_fma_f32 v[158:159], v[174:175], v[8:9], v[158:159]
	ds_read_b128 v[172:175], v167 offset:416
	s_waitcnt lgkmcnt(3)
	v_max_f32_e32 v10, 0, v10
	v_max_f32_e32 v11, 0, v11
	v_pk_fma_f32 v[156:157], v[176:177], v[10:11], v[156:157]
	v_max_f32_e32 v12, 0, v12
	v_max_f32_e32 v13, 0, v13
	v_pk_fma_f32 v[154:155], v[178:179], v[12:13], v[154:155]
	ds_read_b128 v[176:179], v167 offset:448
	s_waitcnt lgkmcnt(3)
	v_max_f32_e32 v14, 0, v14
	v_max_f32_e32 v15, 0, v15
	v_pk_fma_f32 v[152:153], v[180:181], v[14:15], v[152:153]
	v_max_f32_e32 v16, 0, v16
	v_max_f32_e32 v17, 0, v17
	v_pk_fma_f32 v[150:151], v[182:183], v[16:17], v[150:151]
	ds_read_b128 v[180:183], v167 offset:480
	s_waitcnt lgkmcnt(3)
	v_mfma_f32_32x32x16_f16 v[2:17], v[168:171], v[34:37], 0
	ds_read_b128 v[168:171], v184 offset:1536
	s_waitcnt lgkmcnt(3)
	v_mfma_f32_32x32x16_f16 v[2:17], v[172:175], v[38:41], v[2:17]
	ds_read_b128 v[172:175], v184 offset:1568
	s_waitcnt lgkmcnt(3)
	v_mfma_f32_32x32x16_f16 v[2:17], v[176:179], v[42:45], v[2:17]
	ds_read_b128 v[176:179], v184 offset:1600
	s_waitcnt lgkmcnt(3)
	v_mfma_f32_32x32x16_f16 v[2:17], v[180:183], v[46:49], v[2:17]
	ds_read_b128 v[180:183], v184 offset:1632
	s_nop 10
	s_waitcnt lgkmcnt(3)
	v_max_f32_e32 v2, 0, v2
	v_max_f32_e32 v3, 0, v3
	v_pk_fma_f32 v[164:165], v[168:169], v[2:3], v[164:165]
	v_max_f32_e32 v4, 0, v4
	v_max_f32_e32 v5, 0, v5
	v_pk_fma_f32 v[162:163], v[170:171], v[4:5], v[162:163]
	ds_read_b128 v[168:171], v167 offset:512
	s_waitcnt lgkmcnt(3)
	v_max_f32_e32 v6, 0, v6
	v_max_f32_e32 v7, 0, v7
	v_pk_fma_f32 v[160:161], v[172:173], v[6:7], v[160:161]
	v_max_f32_e32 v8, 0, v8
	v_max_f32_e32 v9, 0, v9
	v_pk_fma_f32 v[158:159], v[174:175], v[8:9], v[158:159]
	ds_read_b128 v[172:175], v167 offset:544
	s_waitcnt lgkmcnt(3)
	v_max_f32_e32 v10, 0, v10
	v_max_f32_e32 v11, 0, v11
	v_pk_fma_f32 v[156:157], v[176:177], v[10:11], v[156:157]
	v_max_f32_e32 v12, 0, v12
	v_max_f32_e32 v13, 0, v13
	v_pk_fma_f32 v[154:155], v[178:179], v[12:13], v[154:155]
	ds_read_b128 v[176:179], v167 offset:576
	s_waitcnt lgkmcnt(3)
	v_max_f32_e32 v14, 0, v14
	v_max_f32_e32 v15, 0, v15
	v_pk_fma_f32 v[152:153], v[180:181], v[14:15], v[152:153]
	v_max_f32_e32 v16, 0, v16
	v_max_f32_e32 v17, 0, v17
	v_pk_fma_f32 v[150:151], v[182:183], v[16:17], v[150:151]
	ds_read_b128 v[180:183], v167 offset:608
	s_waitcnt lgkmcnt(3)
	v_mfma_f32_32x32x16_f16 v[2:17], v[168:171], v[34:37], 0
	ds_read_b128 v[168:171], v184 offset:2048
	s_waitcnt lgkmcnt(3)
	v_mfma_f32_32x32x16_f16 v[2:17], v[172:175], v[38:41], v[2:17]
	ds_read_b128 v[172:175], v184 offset:2080
	s_waitcnt lgkmcnt(3)
	v_mfma_f32_32x32x16_f16 v[2:17], v[176:179], v[42:45], v[2:17]
	ds_read_b128 v[176:179], v184 offset:2112
	s_waitcnt lgkmcnt(3)
	v_mfma_f32_32x32x16_f16 v[2:17], v[180:183], v[46:49], v[2:17]
	ds_read_b128 v[180:183], v184 offset:2144
	s_nop 10
	s_waitcnt lgkmcnt(3)
	v_max_f32_e32 v2, 0, v2
	v_max_f32_e32 v3, 0, v3
	v_pk_fma_f32 v[164:165], v[168:169], v[2:3], v[164:165]
	v_max_f32_e32 v4, 0, v4
	v_max_f32_e32 v5, 0, v5
	v_pk_fma_f32 v[162:163], v[170:171], v[4:5], v[162:163]
	ds_read_b128 v[168:171], v167 offset:640
	s_waitcnt lgkmcnt(3)
	v_max_f32_e32 v6, 0, v6
	v_max_f32_e32 v7, 0, v7
	v_pk_fma_f32 v[160:161], v[172:173], v[6:7], v[160:161]
	v_max_f32_e32 v8, 0, v8
	v_max_f32_e32 v9, 0, v9
	v_pk_fma_f32 v[158:159], v[174:175], v[8:9], v[158:159]
	ds_read_b128 v[172:175], v167 offset:672
	s_waitcnt lgkmcnt(3)
	v_max_f32_e32 v10, 0, v10
	v_max_f32_e32 v11, 0, v11
	v_pk_fma_f32 v[156:157], v[176:177], v[10:11], v[156:157]
	v_max_f32_e32 v12, 0, v12
	v_max_f32_e32 v13, 0, v13
	v_pk_fma_f32 v[154:155], v[178:179], v[12:13], v[154:155]
	ds_read_b128 v[176:179], v167 offset:704
	s_waitcnt lgkmcnt(3)
	v_max_f32_e32 v14, 0, v14
	v_max_f32_e32 v15, 0, v15
	v_pk_fma_f32 v[152:153], v[180:181], v[14:15], v[152:153]
	v_max_f32_e32 v16, 0, v16
	v_max_f32_e32 v17, 0, v17
	v_pk_fma_f32 v[150:151], v[182:183], v[16:17], v[150:151]
	ds_read_b128 v[180:183], v167 offset:736
	s_waitcnt lgkmcnt(3)
	v_mfma_f32_32x32x16_f16 v[2:17], v[168:171], v[34:37], 0
	ds_read_b128 v[168:171], v184 offset:2560
	s_waitcnt lgkmcnt(3)
	v_mfma_f32_32x32x16_f16 v[2:17], v[172:175], v[38:41], v[2:17]
	ds_read_b128 v[172:175], v184 offset:2592
	s_waitcnt lgkmcnt(3)
	v_mfma_f32_32x32x16_f16 v[2:17], v[176:179], v[42:45], v[2:17]
	ds_read_b128 v[176:179], v184 offset:2624
	s_waitcnt lgkmcnt(3)
	v_mfma_f32_32x32x16_f16 v[2:17], v[180:183], v[46:49], v[2:17]
	ds_read_b128 v[180:183], v184 offset:2656
	s_nop 10
	s_waitcnt lgkmcnt(3)
	v_max_f32_e32 v2, 0, v2
	v_max_f32_e32 v3, 0, v3
	v_pk_fma_f32 v[164:165], v[168:169], v[2:3], v[164:165]
	v_max_f32_e32 v4, 0, v4
	v_max_f32_e32 v5, 0, v5
	v_pk_fma_f32 v[162:163], v[170:171], v[4:5], v[162:163]
	ds_read_b128 v[168:171], v167 offset:768
	s_waitcnt lgkmcnt(3)
	v_max_f32_e32 v6, 0, v6
	v_max_f32_e32 v7, 0, v7
	v_pk_fma_f32 v[160:161], v[172:173], v[6:7], v[160:161]
	v_max_f32_e32 v8, 0, v8
	v_max_f32_e32 v9, 0, v9
	v_pk_fma_f32 v[158:159], v[174:175], v[8:9], v[158:159]
	ds_read_b128 v[172:175], v167 offset:800
	s_waitcnt lgkmcnt(3)
	v_max_f32_e32 v10, 0, v10
	v_max_f32_e32 v11, 0, v11
	v_pk_fma_f32 v[156:157], v[176:177], v[10:11], v[156:157]
	v_max_f32_e32 v12, 0, v12
	v_max_f32_e32 v13, 0, v13
	v_pk_fma_f32 v[154:155], v[178:179], v[12:13], v[154:155]
	ds_read_b128 v[176:179], v167 offset:832
	s_waitcnt lgkmcnt(3)
	v_max_f32_e32 v14, 0, v14
	v_max_f32_e32 v15, 0, v15
	v_pk_fma_f32 v[152:153], v[180:181], v[14:15], v[152:153]
	v_max_f32_e32 v16, 0, v16
	v_max_f32_e32 v17, 0, v17
	v_pk_fma_f32 v[150:151], v[182:183], v[16:17], v[150:151]
	ds_read_b128 v[180:183], v167 offset:864
	s_waitcnt lgkmcnt(3)
	v_mfma_f32_32x32x16_f16 v[2:17], v[168:171], v[34:37], 0
	ds_read_b128 v[168:171], v184 offset:3072
	s_waitcnt lgkmcnt(3)
	v_mfma_f32_32x32x16_f16 v[2:17], v[172:175], v[38:41], v[2:17]
	ds_read_b128 v[172:175], v184 offset:3104
	s_waitcnt lgkmcnt(3)
	v_mfma_f32_32x32x16_f16 v[2:17], v[176:179], v[42:45], v[2:17]
	ds_read_b128 v[176:179], v184 offset:3136
	s_waitcnt lgkmcnt(3)
	v_mfma_f32_32x32x16_f16 v[2:17], v[180:183], v[46:49], v[2:17]
	ds_read_b128 v[180:183], v184 offset:3168
	s_nop 10
	s_waitcnt lgkmcnt(3)
	v_max_f32_e32 v2, 0, v2
	v_max_f32_e32 v3, 0, v3
	v_pk_fma_f32 v[164:165], v[168:169], v[2:3], v[164:165]
	v_max_f32_e32 v4, 0, v4
	v_max_f32_e32 v5, 0, v5
	v_pk_fma_f32 v[162:163], v[170:171], v[4:5], v[162:163]
	ds_read_b128 v[168:171], v167 offset:896
	s_waitcnt lgkmcnt(3)
	v_max_f32_e32 v6, 0, v6
	v_max_f32_e32 v7, 0, v7
	v_pk_fma_f32 v[160:161], v[172:173], v[6:7], v[160:161]
	v_max_f32_e32 v8, 0, v8
	v_max_f32_e32 v9, 0, v9
	v_pk_fma_f32 v[158:159], v[174:175], v[8:9], v[158:159]
	ds_read_b128 v[172:175], v167 offset:928
	s_waitcnt lgkmcnt(3)
	v_max_f32_e32 v10, 0, v10
	v_max_f32_e32 v11, 0, v11
	v_pk_fma_f32 v[156:157], v[176:177], v[10:11], v[156:157]
	v_max_f32_e32 v12, 0, v12
	v_max_f32_e32 v13, 0, v13
	v_pk_fma_f32 v[154:155], v[178:179], v[12:13], v[154:155]
	ds_read_b128 v[176:179], v167 offset:960
	s_waitcnt lgkmcnt(3)
	v_max_f32_e32 v14, 0, v14
	v_max_f32_e32 v15, 0, v15
	v_pk_fma_f32 v[152:153], v[180:181], v[14:15], v[152:153]
	v_max_f32_e32 v16, 0, v16
	v_max_f32_e32 v17, 0, v17
	v_pk_fma_f32 v[150:151], v[182:183], v[16:17], v[150:151]
	ds_read_b128 v[180:183], v167 offset:992
	s_waitcnt lgkmcnt(3)
	v_mfma_f32_32x32x16_f16 v[2:17], v[168:171], v[34:37], 0
	ds_read_b128 v[168:171], v184 offset:3584
	s_waitcnt lgkmcnt(3)
	v_mfma_f32_32x32x16_f16 v[2:17], v[172:175], v[38:41], v[2:17]
	ds_read_b128 v[172:175], v184 offset:3616
	s_waitcnt lgkmcnt(3)
	v_mfma_f32_32x32x16_f16 v[2:17], v[176:179], v[42:45], v[2:17]
	ds_read_b128 v[176:179], v184 offset:3648
	s_waitcnt lgkmcnt(3)
	v_mfma_f32_32x32x16_f16 v[2:17], v[180:183], v[46:49], v[2:17]
	ds_read_b128 v[180:183], v184 offset:3680
	s_nop 10
	s_waitcnt lgkmcnt(3)
	v_max_f32_e32 v2, 0, v2
	v_max_f32_e32 v3, 0, v3
	v_pk_fma_f32 v[164:165], v[168:169], v[2:3], v[164:165]
	v_max_f32_e32 v4, 0, v4
	v_max_f32_e32 v5, 0, v5
	v_pk_fma_f32 v[162:163], v[170:171], v[4:5], v[162:163]
	s_waitcnt lgkmcnt(2)
	v_max_f32_e32 v6, 0, v6
	v_max_f32_e32 v7, 0, v7
	v_pk_fma_f32 v[160:161], v[172:173], v[6:7], v[160:161]
	v_max_f32_e32 v8, 0, v8
	v_max_f32_e32 v9, 0, v9
	v_pk_fma_f32 v[158:159], v[174:175], v[8:9], v[158:159]
	s_waitcnt lgkmcnt(1)
	v_max_f32_e32 v10, 0, v10
	v_max_f32_e32 v11, 0, v11
	v_pk_fma_f32 v[156:157], v[176:177], v[10:11], v[156:157]
	v_max_f32_e32 v12, 0, v12
	v_max_f32_e32 v13, 0, v13
	v_pk_fma_f32 v[154:155], v[178:179], v[12:13], v[154:155]
	s_waitcnt lgkmcnt(0)
	v_max_f32_e32 v14, 0, v14
	v_max_f32_e32 v15, 0, v15
	v_pk_fma_f32 v[152:153], v[180:181], v[14:15], v[152:153]
	v_max_f32_e32 v16, 0, v16
	v_max_f32_e32 v17, 0, v17
	v_pk_fma_f32 v[150:151], v[182:183], v[16:17], v[150:151]
	s_mov_b64 s[10:11], 0x80
	v_lshl_add_u64 v[2:3], v[146:147], 0, s[10:11]
	v_lshl_add_u64 v[4:5], v[2:3], 0, v[198:199]
	global_store_dword v[4:5], v165, off nt
	v_lshl_add_u64 v[4:5], v[2:3], 0, v[200:201]
	global_store_dword v[4:5], v162, off nt
	v_lshl_add_u64 v[4:5], v[2:3], 0, v[202:203]
	global_store_dword v[4:5], v163, off nt
	v_lshl_add_u64 v[4:5], v[2:3], 0, v[204:205]
	global_store_dword v[4:5], v160, off nt
	v_lshl_add_u64 v[4:5], v[2:3], 0, v[206:207]
	global_store_dword v[4:5], v161, off nt
	v_lshl_add_u64 v[4:5], v[2:3], 0, v[208:209]
	global_store_dword v[4:5], v158, off nt
	v_lshl_add_u64 v[4:5], v[2:3], 0, v[210:211]
	global_store_dword v[4:5], v159, off nt
	v_lshl_add_u64 v[4:5], v[2:3], 0, v[212:213]
	global_store_dword v[4:5], v156, off nt
	v_lshl_add_u64 v[4:5], v[2:3], 0, v[214:215]
	global_store_dword v[4:5], v157, off nt
	v_lshl_add_u64 v[4:5], v[2:3], 0, v[216:217]
	global_store_dword v[4:5], v154, off nt
	v_lshl_add_u64 v[4:5], v[2:3], 0, v[218:219]
	global_store_dword v[4:5], v155, off nt
	v_lshl_add_u64 v[4:5], v[2:3], 0, v[220:221]
	global_store_dword v[4:5], v152, off nt
	v_lshl_add_u64 v[4:5], v[2:3], 0, v[222:223]
	global_store_dword v[4:5], v153, off nt
	v_lshl_add_u64 v[4:5], v[2:3], 0, v[224:225]
	v_lshl_add_u64 v[2:3], v[2:3], 0, v[230:231]
	s_add_i32 s14, s14, 1
	s_and_b64 vcc, exec, s[8:9]
	global_store_dword v[148:149], v164, off offset:128 nt
	global_store_dword v[4:5], v150, off nt
	global_store_dword v[2:3], v151, off nt
	s_cbranch_vccnz .LBB0_1007
	v_mov_b64_e32 v[176:177], v[128:129]
	v_mov_b64_e32 v[172:173], v[124:125]
	v_mov_b64_e32 v[168:169], v[120:121]
	v_mov_b64_e32 v[164:165], v[116:117]
	v_mov_b64_e32 v[160:161], v[112:113]
	v_mov_b64_e32 v[156:157], v[108:109]
	v_mov_b64_e32 v[152:153], v[104:105]
	v_mov_b64_e32 v[148:149], v[100:101]
	v_mov_b64_e32 v[14:15], v[94:95]
	v_mov_b64_e32 v[10:11], v[90:91]
	v_mov_b64_e32 v[6:7], v[86:87]
	v_mov_b64_e32 v[2:3], v[82:83]
	v_mov_b64_e32 v[46:47], v[66:67]
	v_mov_b64_e32 v[42:43], v[70:71]
	v_mov_b64_e32 v[38:39], v[74:75]
	v_mov_b64_e32 v[34:35], v[78:79]
	v_mov_b64_e32 v[30:31], v[50:51]
	v_mov_b64_e32 v[26:27], v[54:55]
	v_mov_b64_e32 v[22:23], v[58:59]
	v_mov_b64_e32 v[18:19], v[62:63]
	v_mov_b64_e32 v[184:185], v[132:133]
	v_mov_b64_e32 v[180:181], v[136:137]
	v_mov_b64_e32 v[192:193], v[140:141]
	v_mov_b64_e32 v[188:189], v[144:145]
	v_mov_b64_e32 v[174:175], v[126:127]
	v_mov_b64_e32 v[170:171], v[122:123]
	v_mov_b64_e32 v[166:167], v[118:119]
	v_mov_b64_e32 v[162:163], v[114:115]
	v_mov_b64_e32 v[158:159], v[110:111]
	v_mov_b64_e32 v[154:155], v[106:107]
	v_mov_b64_e32 v[150:151], v[102:103]
	v_mov_b64_e32 v[146:147], v[98:99]
	v_mov_b64_e32 v[16:17], v[96:97]
	v_mov_b64_e32 v[12:13], v[92:93]
	v_mov_b64_e32 v[8:9], v[88:89]
	v_mov_b64_e32 v[4:5], v[84:85]
	v_mov_b64_e32 v[48:49], v[68:69]
	v_mov_b64_e32 v[44:45], v[72:73]
	v_mov_b64_e32 v[40:41], v[76:77]
	v_mov_b64_e32 v[36:37], v[80:81]
	v_mov_b64_e32 v[32:33], v[52:53]
	v_mov_b64_e32 v[28:29], v[56:57]
	v_mov_b64_e32 v[24:25], v[60:61]
	v_mov_b64_e32 v[20:21], v[64:65]
	v_mov_b64_e32 v[182:183], v[130:131]
	v_mov_b64_e32 v[178:179], v[134:135]
	v_mov_b64_e32 v[190:191], v[138:139]
	v_mov_b64_e32 v[186:187], v[142:143]
	v_mov_b64_e32 v[236:237], v[234:235]
	s_branch .LBB0_995
